# attention: running max folded into the QK MFMA accumulator init (C = -m block, same lazy-rescale rule), removing 32 v_sub per tile; P fragments double-buffered
# speedup vs baseline: 1.0157x; 1.0157x over previous
; #define LAS __attribute__((address_space(3)))
; __device__ __forceinline__ void lds_barrier() { asm volatile("s_waitcnt lgkmcnt(0)" ::: "memory"); __builtin_amdgcn_s_barrier(); asm volatile("" ::: "memory"); }
; __device__ __forceinline__ u32x4 gload16_asm(const void* p) { u32x4 r; asm volatile("global_load_dwordx4 %0, %1, off" : "=v"(r) : "v"(p) : "memory"); return r; }
; __device__ __forceinline__ void attn_phase(const Args& a, LAS unsigned char* lds, const bf16* Qn, const bf16* Kn, const bf16* Vt, bf16* O, float* stash, int tid, int lane, int wave) {
;     ...
;             const bf16* Qp = Qn + ((size_t)(bh * 2 + c) * SEQ + 256 * qb + 32 * wave + n32) * 64 + 8 * hi;
;             bf16x8 qf[4];
; #pragma unroll
;             for (int ds = 0; ds < 4; ++ds) qf[ds] = *(const bf16x8*)(Qp + 16 * ds);
;             const bf16* Kp = Kn + (size_t)(bh * 2 + c) * SEQ * 64 + tid * 8;
;             const bf16* Vp = Vt + (size_t)bh * 128 * SEQ + (size_t)(tid >> 3) * SEQ + 8 * (tid & 7);
;             const int kofs = (tid >> 3) * 144 + (tid & 7) * 16;
;             f32x16 o[4];
; #pragma unroll
;             for (int i = 0; i < 4; ++i)
; #pragma unroll
;                 for (int r = 0; r < 16; ++r) o[i][r] = 0.f;
;             float mrun = -INFINITY, lsum = 0.f;
;             u32x4 kreg[2], vreg0[2], vreg1[2];
;             kreg[0] = gload16_asm(Kp); vreg0[0] = gload16_asm(Vp); vreg1[0] = gload16_asm(Vp + (size_t)64 * SEQ);
;             kreg[1] = gload16_asm(Kp + 4096); vreg0[1] = gload16_asm(Vp + 64); vreg1[1] = gload16_asm(Vp + (size_t)64 * SEQ + 64);
;             asm volatile("" :: "v"(qf[0]), "v"(qf[1]), "v"(qf[2]), "v"(qf[3]));
;             asm volatile("s_waitcnt vmcnt(3)" ::: "memory");
;             *(LAS u32x4*)(lds + kofs) = kreg[0]; *(LAS u32x4*)(lds + AT_KB + kofs) = vreg0[0]; *(LAS u32x4*)(lds + AT_KB + 64 * 144 + kofs) = vreg1[0];
;             lds_barrier();
.LBB0_105:
	v_readlane_b32 s16, v255, 5
	s_or_b32 s22, s2, s16
	v_readlane_b32 s2, v255, 13
	s_add_i32 s2, s22, s2
	s_xor_b64 s[16:17], s[20:21], -1
	v_lshl_add_u64 v[2:3], v[158:159], 0, s[2:3]
	v_lshlrev_b64 v[2:3], 7, v[2:3]
	v_lshl_add_u64 v[2:3], v[162:163], 0, v[2:3]
	global_load_dwordx4 v[112:115], v[2:3], off
	global_load_dwordx4 v[116:119], v[2:3], off offset:32
	global_load_dwordx4 v[120:123], v[2:3], off offset:64
	global_load_dwordx4 v[124:127], v[2:3], off offset:96
	s_lshl_b32 s2, s22, 7
	v_lshl_add_u64 v[32:33], v[164:165], 0, s[2:3]
	global_load_dwordx4 v[132:135], v[32:33], off
	global_load_dwordx4 v[140:143], v[174:175], off
	s_mov_b64 s[20:21], 0x2000
	global_load_dwordx4 v[148:151], v[176:177], off
	v_lshl_add_u64 v[34:35], v[32:33], 0, s[20:21]
	global_load_dwordx4 v[128:131], v[34:35], off
	global_load_dwordx4 v[136:139], v[178:179], off
	global_load_dwordx4 v[144:147], v[180:181], off
	v_mov_b32_e32 v14, v1
	v_mov_b32_e32 v15, v1
	s_mov_b64 s[20:21], 0x6000
	v_mov_b32_e32 v0, v1
	v_mov_b32_e32 v2, v1
	v_mov_b32_e32 v3, v1
	v_mov_b32_e32 v4, v1
	v_mov_b32_e32 v5, v1
	v_mov_b32_e32 v6, v1
	v_mov_b32_e32 v7, v1
	v_mov_b32_e32 v8, v1
	v_mov_b32_e32 v9, v1
	v_mov_b32_e32 v10, v1
	v_mov_b32_e32 v11, v1
	v_mov_b32_e32 v12, v1
	v_mov_b32_e32 v13, v1
	v_mov_b64_e32 v[30:31], v[14:15]
	v_lshl_add_u64 v[192:193], v[32:33], 0, s[20:21]
	v_mov_b64_e32 v[46:47], v[14:15]
	v_mov_b64_e32 v[62:63], v[14:15]
	v_mov_b64_e32 v[78:79], v[14:15]
	v_mov_b32_e32 v197, 0
	v_mov_b32_e32 v194, 0
	v_mov_b32_e32 v226, 0
	v_mov_b32_e32 v227, 0
	v_mov_b32_e32 v228, 0
	v_mov_b32_e32 v229, 0
	v_mov_b32_e32 v230, 0
	v_mov_b32_e32 v231, 0
	v_mov_b32_e32 v232, 0
	v_mov_b32_e32 v233, 0
	v_mov_b32_e32 v234, 0
	v_mov_b32_e32 v235, 0
	v_mov_b32_e32 v236, 0
	v_mov_b32_e32 v237, 0
	v_mov_b32_e32 v238, 0
	v_mov_b32_e32 v239, 0
	v_mov_b32_e32 v240, 0
	v_mov_b32_e32 v241, 0
	s_mov_b64 s[100:101], -1
	v_mov_b64_e32 v[188:189], v[186:187]
	v_mov_b64_e32 v[190:191], v[184:185]
	v_mov_b64_e32 v[28:29], v[12:13]
	v_mov_b64_e32 v[26:27], v[10:11]
	v_mov_b64_e32 v[24:25], v[8:9]
	v_mov_b64_e32 v[22:23], v[6:7]
	v_mov_b64_e32 v[20:21], v[4:5]
	v_mov_b64_e32 v[18:19], v[2:3]
	v_mov_b64_e32 v[16:17], v[0:1]
	v_mov_b64_e32 v[44:45], v[12:13]
	v_mov_b64_e32 v[42:43], v[10:11]
	v_mov_b64_e32 v[40:41], v[8:9]
	v_mov_b64_e32 v[38:39], v[6:7]
	v_mov_b64_e32 v[36:37], v[4:5]
	v_mov_b64_e32 v[34:35], v[2:3]
	v_mov_b64_e32 v[32:33], v[0:1]
	v_mov_b64_e32 v[60:61], v[12:13]
	v_mov_b64_e32 v[58:59], v[10:11]
	v_mov_b64_e32 v[56:57], v[8:9]
	v_mov_b64_e32 v[54:55], v[6:7]
	v_mov_b64_e32 v[52:53], v[4:5]
	v_mov_b64_e32 v[50:51], v[2:3]
	v_mov_b64_e32 v[48:49], v[0:1]
	v_mov_b64_e32 v[76:77], v[12:13]
	v_mov_b64_e32 v[74:75], v[10:11]
	v_mov_b64_e32 v[72:73], v[8:9]
	v_mov_b64_e32 v[70:71], v[6:7]
	v_mov_b64_e32 v[68:69], v[4:5]
	v_mov_b64_e32 v[66:67], v[2:3]
	v_mov_b64_e32 v[64:65], v[0:1]
	s_mov_b32 s2, 0
	s_waitcnt vmcnt(0)
	s_waitcnt vmcnt(3)
	ds_write_b128 v195, v[132:135]
	ds_write_b128 v195, v[140:143] offset:9216
	ds_write_b128 v195, v[148:151] offset:18432
	s_waitcnt lgkmcnt(0)
	s_barrier

; __device__ __forceinline__ void attn_phase(const Args& a, LAS unsigned char* lds, const bf16* Qn, const bf16* Kn, const bf16* Vt, bf16* O, float* stash, int tid, int lane, int wave) {
;     ...
;                 if (t + 2 < NT) { kreg[hh] = gload16_asm(Kp + (size_t)(t + 2) * 4096); vreg0[hh] = gload16_asm(Vp + 64 * (t + 2)); vreg1[hh] = gload16_asm(Vp + (size_t)64 * SEQ + 64 * (t + 2)); }
;                 if (t <= td) {
;                     const LAS unsigned char* kb = lds + (t & 1) * AT_BUF + n32 * 144 + hi * 16;
;                     f32x16 p0, p1;
; #pragma unroll
;                     for (int r = 0; r < 16; ++r) { p0[r] = 0.f; p1[r] = 0.f; }
;                     bf16x8 kf0[4], kf1[4];
; #pragma unroll
;                     for (int ds = 0; ds < 4; ++ds) { kf0[ds] = *(const LAS bf16x8*)(kb + ds * 32); kf1[ds] = *(const LAS bf16x8*)(kb + 32 * 144 + ds * 32); }
;                     const LAS unsigned char* vb = lds + (t & 1) * AT_BUF + AT_KB + n32 * 144 + hi * 16;
;                     bf16x8 vf[2][4];
; #pragma unroll
;                     for (int i = 0; i < 4; ++i) vf[0][i] = *(const LAS bf16x8*)(vb + i * 32 * 144);
;                     __builtin_amdgcn_sched_barrier(0);
;                     #pragma unroll
;                     for (int ds = 0; ds < 4; ++ds) {
;                         p0 = __builtin_amdgcn_mfma_f32_32x32x16_bf16(kf0[ds], qf[ds], p0, 0, 0, 0);
;                         p1 = __builtin_amdgcn_mfma_f32_32x32x16_bf16(kf1[ds], qf[ds], p1, 0, 0, 0);
;                     }
;                                         __builtin_amdgcn_sched_barrier(0);
;                     if (t == td) {
;                         asm volatile("" ::: "memory");
; #pragma unroll
;                         for (int r = 0; r < 16; ++r) { const int key = (r & 3) + 8 * (r >> 2) + 4 * hi; if (key > qloc) p0[r] = -INFINITY; if (key + 32 > qloc) p1[r] = -INFINITY; }
;                     }
;                     asm volatile("s_nop 15\n\ts_nop 7" : "+v"(p0), "+v"(p1));
;                     float mx, mxb;
;                     mx = max3f(p0[0], p0[1], p1[0]); mxb = max3f(p0[2], p0[3], p1[1]); mx = max3f(mx, p1[2], p1[3]);
; #pragma unroll
;                     for (int r = 4; r < 16; r += 4) { mx = max3f(mx, p0[r], p0[r + 1]); mxb = max3f(mxb, p0[r + 2], p0[r + 3]); mx = max3f(mx, p1[r], p1[r + 1]); mxb = max3f(mxb, p1[r + 2], p1[r + 3]); }
.LBB0_110:
	v_add_u32_e32 v0, v161, v160
	ds_read_b128 v[80:83], v0
	ds_read_b128 v[198:201], v0 offset:32
	ds_read_b128 v[84:87], v0 offset:4608
	ds_read_b128 v[202:205], v0 offset:4640
	ds_read_b128 v[206:209], v0 offset:64
	ds_read_b128 v[210:213], v0 offset:96
	ds_read_b128 v[218:221], v0 offset:4672
	ds_read_b128 v[222:225], v0 offset:4704
	ds_read_b128 v[152:155], v0 offset:9216
	ds_read_b128 v[10:13], v0 offset:13824
	ds_read_b128 v[6:9], v0 offset:18432
	ds_read_b128 v[2:5], v0 offset:23040
	s_waitcnt lgkmcnt(11)
	v_mfma_f32_32x32x16_bf16 v[96:111], v[80:83], v[112:115], v[226:241]
	s_waitcnt lgkmcnt(9)
	v_mfma_f32_32x32x16_bf16 v[80:95], v[84:87], v[112:115], v[226:241]
	v_mfma_f32_32x32x16_bf16 v[96:111], v[198:201], v[116:119], v[96:111]
	s_waitcnt lgkmcnt(8)
	v_mfma_f32_32x32x16_bf16 v[80:95], v[202:205], v[116:119], v[80:95]
	s_waitcnt lgkmcnt(7)
	v_mfma_f32_32x32x16_bf16 v[96:111], v[206:209], v[120:123], v[96:111]
	s_waitcnt lgkmcnt(5)
	v_mfma_f32_32x32x16_bf16 v[80:95], v[218:221], v[120:123], v[80:95]
	v_mfma_f32_32x32x16_bf16 v[96:111], v[210:213], v[124:127], v[96:111]
	s_waitcnt lgkmcnt(4)
	v_mfma_f32_32x32x16_bf16 v[80:95], v[222:225], v[124:127], v[80:95]
	ds_read_b128 v[198:201], v0 offset:9248
	ds_read_b128 v[202:205], v0 offset:13856
	ds_read_b128 v[206:209], v0 offset:18464
	ds_read_b128 v[210:213], v0 offset:23072
	s_nop 7
	s_cmp_lg_u32 s30, s2
	s_cbranch_scc1 .Lat_nodiag_a
	v_cndmask_b32_e64 v14, v96, v248, s[42:43]
	v_cndmask_b32_e64 v80, v80, v248, s[44:45]
	v_cndmask_b32_e64 v97, v248, v97, s[46:47]
	v_cndmask_b32_e64 v96, v14, v96, s[46:47]
	v_cndmask_b32_e64 v81, v81, v248, s[48:49]
	v_cndmask_b32_e64 v98, v98, v248, s[50:51]
	v_cndmask_b32_e64 v82, v82, v248, s[52:53]
	v_cndmask_b32_e64 v99, v99, v248, s[54:55]
	v_cndmask_b32_e64 v83, v83, v248, s[56:57]
	v_cndmask_b32_e64 v100, v100, v248, s[58:59]
	v_cndmask_b32_e64 v84, v84, v248, s[60:61]
	v_cndmask_b32_e64 v101, v101, v248, s[62:63]
	v_cndmask_b32_e64 v85, v85, v248, s[64:65]
	v_cndmask_b32_e64 v102, v102, v248, s[66:67]
	v_cndmask_b32_e64 v86, v86, v248, s[68:69]
	v_cndmask_b32_e64 v103, v103, v248, s[70:71]
	v_cndmask_b32_e64 v87, v87, v248, s[72:73]
	v_cndmask_b32_e64 v104, v104, v248, s[74:75]
	v_cndmask_b32_e64 v88, v88, v248, s[76:77]
	v_cndmask_b32_e64 v105, v105, v248, s[78:79]
	v_cndmask_b32_e64 v89, v89, v248, s[80:81]
	v_cndmask_b32_e64 v106, v106, v248, s[82:83]
	v_cndmask_b32_e64 v90, v90, v248, s[84:85]
	v_cndmask_b32_e64 v107, v107, v248, s[86:87]
	v_cndmask_b32_e64 v91, v91, v248, s[88:89]
	v_cndmask_b32_e64 v108, v108, v248, s[90:91]
	v_cndmask_b32_e64 v92, v92, v248, s[92:93]
	v_cndmask_b32_e64 v109, v109, v248, s[94:95]
	v_cndmask_b32_e64 v93, v93, v248, s[96:97]
	v_cndmask_b32_e64 v110, v110, v248, s[6:7]
	v_cndmask_b32_e64 v94, v94, v248, s[8:9]
	v_cndmask_b32_e64 v111, v111, v248, s[10:11]
	v_cndmask_b32_e64 v95, v95, v248, s[12:13]
.Lat_nodiag_a:
	v_max3_f32 v14, v96, v97, v80
	v_max3_f32 v15, v98, v99, v81
	v_max3_f32 v14, v14, v82, v83
	v_max3_f32 v15, v15, v102, v103
	v_max3_f32 v14, v14, v100, v101
	v_max3_f32 v15, v15, v86, v87
	v_max3_f32 v14, v14, v84, v85
	v_max3_f32 v15, v15, v106, v107
	v_max3_f32 v14, v14, v104, v105
	v_max3_f32 v15, v15, v90, v91
	v_max3_f32 v14, v14, v88, v89
	v_max3_f32 v15, v15, v110, v111
	v_max3_f32 v14, v14, v108, v109
	v_max3_f32 v15, v15, v94, v95
	v_max3_f32 v14, v14, v92, v93
	v_max3_f32 v14, v14, v15, v15
	v_mov_b32_e32 v15, v14
	s_nop 1
	v_permlane32_swap_b32_e32 v14, v15
	v_max_f32_e32 v14, v14, v15
	v_cmp_lt_f32_e32 vcc, 0x41000000, v14
	s_or_b64 vcc, vcc, s[100:101]
	s_cbranch_scc0 .Lat_noresc_a
	v_max_f32_e32 v15, 0, v14
	v_cndmask_b32_e64 v15, v15, v14, s[100:101]
	v_exp_f32_e64 v214, -v15
	v_add_f32_e32 v194, v194, v15
	v_cndmask_b32_e64 v214, v214, 0, s[100:101]
	v_pk_mul_f32 v[78:79], v[78:79], v[214:215] op_sel_hi:[1,0]
	v_pk_mul_f32 v[76:77], v[76:77], v[214:215] op_sel_hi:[1,0]
	v_pk_mul_f32 v[74:75], v[74:75], v[214:215] op_sel_hi:[1,0]
	v_pk_mul_f32 v[72:73], v[72:73], v[214:215] op_sel_hi:[1,0]
	v_pk_mul_f32 v[70:71], v[70:71], v[214:215] op_sel_hi:[1,0]
	v_pk_mul_f32 v[68:69], v[68:69], v[214:215] op_sel_hi:[1,0]
	v_pk_mul_f32 v[66:67], v[66:67], v[214:215] op_sel_hi:[1,0]
	v_pk_mul_f32 v[64:65], v[64:65], v[214:215] op_sel_hi:[1,0]
	v_pk_mul_f32 v[62:63], v[62:63], v[214:215] op_sel_hi:[1,0]
	v_pk_mul_f32 v[60:61], v[60:61], v[214:215] op_sel_hi:[1,0]
	v_pk_mul_f32 v[58:59], v[58:59], v[214:215] op_sel_hi:[1,0]
	v_pk_mul_f32 v[56:57], v[56:57], v[214:215] op_sel_hi:[1,0]
	v_pk_mul_f32 v[54:55], v[54:55], v[214:215] op_sel_hi:[1,0]
	v_pk_mul_f32 v[52:53], v[52:53], v[214:215] op_sel_hi:[1,0]
	v_pk_mul_f32 v[50:51], v[50:51], v[214:215] op_sel_hi:[1,0]
	v_pk_mul_f32 v[48:49], v[48:49], v[214:215] op_sel_hi:[1,0]
	v_pk_mul_f32 v[46:47], v[46:47], v[214:215] op_sel_hi:[1,0]
	v_pk_mul_f32 v[44:45], v[44:45], v[214:215] op_sel_hi:[1,0]
	v_pk_mul_f32 v[42:43], v[42:43], v[214:215] op_sel_hi:[1,0]
	v_pk_mul_f32 v[40:41], v[40:41], v[214:215] op_sel_hi:[1,0]
	v_pk_mul_f32 v[38:39], v[38:39], v[214:215] op_sel_hi:[1,0]
	v_pk_mul_f32 v[36:37], v[36:37], v[214:215] op_sel_hi:[1,0]
	v_pk_mul_f32 v[34:35], v[34:35], v[214:215] op_sel_hi:[1,0]
	v_pk_mul_f32 v[32:33], v[32:33], v[214:215] op_sel_hi:[1,0]
	v_pk_mul_f32 v[30:31], v[30:31], v[214:215] op_sel_hi:[1,0]
	v_pk_mul_f32 v[28:29], v[28:29], v[214:215] op_sel_hi:[1,0]
	v_pk_mul_f32 v[26:27], v[26:27], v[214:215] op_sel_hi:[1,0]
	v_pk_mul_f32 v[24:25], v[24:25], v[214:215] op_sel_hi:[1,0]
	v_pk_mul_f32 v[22:23], v[22:23], v[214:215] op_sel_hi:[1,0]
	v_pk_mul_f32 v[20:21], v[20:21], v[214:215] op_sel_hi:[1,0]
; __device__ __forceinline__ void attn_phase(const Args& a, LAS unsigned char* lds, const bf16* Qn, const bf16* Kn, const bf16* Vt, bf16* O, float* stash, int tid, int lane, int wave) {
;     ...
;                         const float alpha = __builtin_amdgcn_exp2f(mrun - mnew);
;                         lsum *= alpha;
; #pragma unroll
;                         for (int i = 0; i < 4; ++i) o[i] = o[i] * alpha;
;                         mrun = mnew;
;                     }
;                     {
;                         const f32x2 mm2 = {mrun, mrun};
; #pragma unroll
;                         for (int r = 0; r < 16; r += 2) { const f32x2 a2 = (f32x2){p0[r], p0[r + 1]} - mm2, b2 = (f32x2){p1[r], p1[r + 1]} - mm2; p0[r] = a2.x; p0[r + 1] = a2.y; p1[r] = b2.x; p1[r + 1] = b2.y; }
;                     }
; #pragma unroll
;                     for (int r = 0; r < 16; ++r) { p0[r] = __builtin_amdgcn_exp2f(p0[r]); p1[r] = __builtin_amdgcn_exp2f(p1[r]); }
;                     {
;                         const f32x16 ps = p0 + p1;
;                         f32x2 s2 = (f32x2){ps[0], ps[1]} + (f32x2){ps[2], ps[3]};
; #pragma unroll
;                         for (int r = 4; r < 16; r += 2) s2 += (f32x2){ps[r], ps[r + 1]};
;                         lsum += s2.x + s2.y;
;                     }
;                     bf16x8 pf[4];
; #pragma unroll
;                     for (int s4 = 0; s4 < 4; ++s4) {
;                         u32x4 w;
;                         if (s4 < 2) { w.x = pk2(p0[8 * s4 + 0], p0[8 * s4 + 1]); w.y = pk2(p0[8 * s4 + 2], p0[8 * s4 + 3]); w.z = pk2(p0[8 * s4 + 4], p0[8 * s4 + 5]); w.w = pk2(p0[8 * s4 + 6], p0[8 * s4 + 7]); }
;                         else { const int q = s4 - 2; w.x = pk2(p1[8 * q + 0], p1[8 * q + 1]); w.y = pk2(p1[8 * q + 2], p1[8 * q + 3]); w.z = pk2(p1[8 * q + 4], p1[8 * q + 5]); w.w = pk2(p1[8 * q + 6], p1[8 * q + 7]); }
;                         pf[s4] = __builtin_bit_cast(bf16x8, w);
;                     }
; #pragma unroll
;                     for (int s4 = 0; s4 < 4; ++s4) {
;                         if (s4 + 1 < 4) {
; #pragma unroll
;                             for (int i = 0; i < 4; ++i) vf[(s4 + 1) & 1][i] = *(const LAS bf16x8*)(vb + i * 32 * 144 + (s4 + 1) * 32);
;                         }
;                         __builtin_amdgcn_sched_barrier(0);
;                         #pragma unroll
	v_pk_mul_f32 v[18:19], v[18:19], v[214:215] op_sel_hi:[1,0]
	v_pk_mul_f32 v[16:17], v[16:17], v[214:215] op_sel_hi:[1,0]
	v_mul_f32_e32 v197, v197, v214
	v_sub_f32_e32 v96, v96, v15
	v_sub_f32_e32 v97, v97, v15
	v_sub_f32_e32 v98, v98, v15
	v_sub_f32_e32 v99, v99, v15
	v_sub_f32_e32 v100, v100, v15
	v_sub_f32_e32 v101, v101, v15
	v_sub_f32_e32 v102, v102, v15
	v_sub_f32_e32 v103, v103, v15
	v_sub_f32_e32 v104, v104, v15
	v_sub_f32_e32 v105, v105, v15
	v_sub_f32_e32 v106, v106, v15
	v_sub_f32_e32 v107, v107, v15
	v_sub_f32_e32 v108, v108, v15
	v_sub_f32_e32 v109, v109, v15
	v_sub_f32_e32 v110, v110, v15
	v_sub_f32_e32 v111, v111, v15
	v_sub_f32_e32 v80, v80, v15
	v_sub_f32_e32 v81, v81, v15
	v_sub_f32_e32 v82, v82, v15
	v_sub_f32_e32 v83, v83, v15
	v_sub_f32_e32 v84, v84, v15
	v_sub_f32_e32 v85, v85, v15
	v_sub_f32_e32 v86, v86, v15
	v_sub_f32_e32 v87, v87, v15
	v_sub_f32_e32 v88, v88, v15
	v_sub_f32_e32 v89, v89, v15
	v_sub_f32_e32 v90, v90, v15
	v_sub_f32_e32 v91, v91, v15
	v_sub_f32_e32 v92, v92, v15
	v_sub_f32_e32 v93, v93, v15
	v_sub_f32_e32 v94, v94, v15
	v_sub_f32_e32 v95, v95, v15
	v_sub_f32_e32 v226, 0, v194
	v_sub_f32_e32 v227, 0, v194
	v_sub_f32_e32 v228, 0, v194
	v_sub_f32_e32 v229, 0, v194
	v_sub_f32_e32 v230, 0, v194
	v_sub_f32_e32 v231, 0, v194
	v_sub_f32_e32 v232, 0, v194
	v_sub_f32_e32 v233, 0, v194
	v_sub_f32_e32 v234, 0, v194
	v_sub_f32_e32 v235, 0, v194
	v_sub_f32_e32 v236, 0, v194
	v_sub_f32_e32 v237, 0, v194
	v_sub_f32_e32 v238, 0, v194
	v_sub_f32_e32 v239, 0, v194
	v_sub_f32_e32 v240, 0, v194
	v_sub_f32_e32 v241, 0, v194
	s_mov_b64 s[100:101], 0
.Lat_noresc_a:
	v_exp_f32_e32 v96, v96
	v_exp_f32_e32 v97, v97
	v_exp_f32_e32 v98, v98
	v_exp_f32_e32 v99, v99
	v_exp_f32_e32 v100, v100
	v_exp_f32_e32 v101, v101
	v_exp_f32_e32 v102, v102
	v_exp_f32_e32 v103, v103
	v_add_f32_e32 v214, v96, v97
	v_add_f32_e32 v215, v98, v99
	v_add_f32_e32 v214, v214, v100
	v_add_f32_e32 v215, v215, v101
	v_add_f32_e32 v214, v214, v102
	v_add_f32_e32 v215, v215, v103
	v_cvt_pk_bf16_f32 v218, v96, v97
	v_cvt_pk_bf16_f32 v219, v98, v99
	v_cvt_pk_bf16_f32 v220, v100, v101
	v_cvt_pk_bf16_f32 v221, v102, v103
	v_add_f32_e32 v197, v197, v214
	v_add_f32_e32 v197, v197, v215
	s_waitcnt lgkmcnt(7)
	v_mfma_f32_32x32x16_bf16 v[64:79], v[152:155], v[218:221], v[64:79]
	v_exp_f32_e32 v104, v104
	v_exp_f32_e32 v105, v105
	v_exp_f32_e32 v106, v106
	v_exp_f32_e32 v107, v107
	v_exp_f32_e32 v108, v108
	s_waitcnt lgkmcnt(6)
	v_mfma_f32_32x32x16_bf16 v[48:63], v[10:13], v[218:221], v[48:63]
	v_exp_f32_e32 v109, v109
	v_exp_f32_e32 v110, v110
	v_exp_f32_e32 v111, v111
	v_add_f32_e32 v214, v104, v105
	v_add_f32_e32 v215, v106, v107
	s_waitcnt lgkmcnt(5)
	v_mfma_f32_32x32x16_bf16 v[32:47], v[6:9], v[218:221], v[32:47]
	v_add_f32_e32 v214, v214, v108
	v_add_f32_e32 v215, v215, v109
	v_add_f32_e32 v214, v214, v110
	v_add_f32_e32 v215, v215, v111
	v_cvt_pk_bf16_f32 v222, v104, v105
	s_waitcnt lgkmcnt(4)
	v_mfma_f32_32x32x16_bf16 v[16:31], v[2:5], v[218:221], v[16:31]
	v_cvt_pk_bf16_f32 v223, v106, v107
	v_cvt_pk_bf16_f32 v224, v108, v109
	v_cvt_pk_bf16_f32 v225, v110, v111
	v_add_f32_e32 v197, v197, v214
	v_add_f32_e32 v197, v197, v215
	ds_read_b128 v[152:155], v0 offset:9280
	ds_read_b128 v[10:13], v0 offset:13888
	ds_read_b128 v[6:9], v0 offset:18496
	ds_read_b128 v[2:5], v0 offset:23104
	s_waitcnt lgkmcnt(7)
	v_mfma_f32_32x32x16_bf16 v[64:79], v[198:201], v[222:225], v[64:79]
	v_exp_f32_e32 v80, v80
	v_exp_f32_e32 v81, v81
	v_exp_f32_e32 v82, v82
	v_exp_f32_e32 v83, v83
	v_exp_f32_e32 v84, v84
	s_waitcnt lgkmcnt(6)
	v_mfma_f32_32x32x16_bf16 v[48:63], v[202:205], v[222:225], v[48:63]
	v_exp_f32_e32 v85, v85
	v_exp_f32_e32 v86, v86
	v_exp_f32_e32 v87, v87
	v_add_f32_e32 v214, v80, v81
	v_add_f32_e32 v215, v82, v83
	s_waitcnt lgkmcnt(5)
	v_mfma_f32_32x32x16_bf16 v[32:47], v[206:209], v[222:225], v[32:47]
	v_add_f32_e32 v214, v214, v84
	v_add_f32_e32 v215, v215, v85
	v_add_f32_e32 v214, v214, v86
	v_add_f32_e32 v215, v215, v87
	v_cvt_pk_bf16_f32 v218, v80, v81
	s_waitcnt lgkmcnt(4)
	v_mfma_f32_32x32x16_bf16 v[16:31], v[210:213], v[222:225], v[16:31]
	v_cvt_pk_bf16_f32 v219, v82, v83
	v_cvt_pk_bf16_f32 v220, v84, v85
	v_cvt_pk_bf16_f32 v221, v86, v87
	v_add_f32_e32 v197, v197, v214
	v_add_f32_e32 v197, v197, v215
	ds_read_b128 v[198:201], v0 offset:9312
	ds_read_b128 v[202:205], v0 offset:13920
	ds_read_b128 v[206:209], v0 offset:18528
	ds_read_b128 v[210:213], v0 offset:23136
	s_waitcnt lgkmcnt(7)
	v_mfma_f32_32x32x16_bf16 v[64:79], v[152:155], v[218:221], v[64:79]
	v_exp_f32_e32 v88, v88
	v_exp_f32_e32 v89, v89
	v_exp_f32_e32 v90, v90
	v_exp_f32_e32 v91, v91
	v_exp_f32_e32 v92, v92
	s_waitcnt lgkmcnt(6)
	v_mfma_f32_32x32x16_bf16 v[48:63], v[10:13], v[218:221], v[48:63]
	v_exp_f32_e32 v93, v93
	v_exp_f32_e32 v94, v94
	v_exp_f32_e32 v95, v95
	v_add_f32_e32 v214, v88, v89
	v_add_f32_e32 v215, v90, v91
	s_waitcnt lgkmcnt(5)
	v_mfma_f32_32x32x16_bf16 v[32:47], v[6:9], v[218:221], v[32:47]
	v_add_f32_e32 v214, v214, v92
	v_add_f32_e32 v215, v215, v93
	v_add_f32_e32 v214, v214, v94
	v_add_f32_e32 v215, v215, v95
	v_cvt_pk_bf16_f32 v222, v88, v89
	s_waitcnt lgkmcnt(4)
	v_mfma_f32_32x32x16_bf16 v[16:31], v[2:5], v[218:221], v[16:31]
	v_cvt_pk_bf16_f32 v223, v90, v91
	v_cvt_pk_bf16_f32 v224, v92, v93
	v_cvt_pk_bf16_f32 v225, v94, v95
	v_add_f32_e32 v197, v197, v214
	v_add_f32_e32 v197, v197, v215
	s_waitcnt lgkmcnt(3)
	v_mfma_f32_32x32x16_bf16 v[64:79], v[198:201], v[222:225], v[64:79]
	s_waitcnt lgkmcnt(2)
	v_mfma_f32_32x32x16_bf16 v[48:63], v[202:205], v[222:225], v[48:63]
	s_waitcnt lgkmcnt(1)
	v_mfma_f32_32x32x16_bf16 v[32:47], v[206:209], v[222:225], v[32:47]
	s_waitcnt lgkmcnt(0)
	v_mfma_f32_32x32x16_bf16 v[16:31], v[210:213], v[222:225], v[16:31]
	s_add_i32 s22, s2, 1
	s_cmp_ge_u32 s22, s33
	s_cbranch_scc1 .LBB0_120

; #define LAS __attribute__((address_space(3)))
; __device__ __forceinline__ u32x4 gload16_asm(const void* p) { u32x4 r; asm volatile("global_load_dwordx4 %0, %1, off" : "=v"(r) : "v"(p) : "memory"); return r; }
; __device__ __forceinline__ void attn_phase(const Args& a, LAS unsigned char* lds, const bf16* Qn, const bf16* Kn, const bf16* Vt, bf16* O, float* stash, int tid, int lane, int wave) {
;     ...
;                 if (t + 2 < NT) { kreg[hh] = gload16_asm(Kp + (size_t)(t + 2) * 4096); vreg0[hh] = gload16_asm(Vp + 64 * (t + 2)); vreg1[hh] = gload16_asm(Vp + (size_t)64 * SEQ + 64 * (t + 2)); }
;                 if (t <= td) {
;                     const LAS unsigned char* kb = lds + (t & 1) * AT_BUF + n32 * 144 + hi * 16;
;                     f32x16 p0, p1;
; #pragma unroll
;                     for (int r = 0; r < 16; ++r) { p0[r] = 0.f; p1[r] = 0.f; }
;                     bf16x8 kf0[4], kf1[4];
; #pragma unroll
;                     for (int ds = 0; ds < 4; ++ds) { kf0[ds] = *(const LAS bf16x8*)(kb + ds * 32); kf1[ds] = *(const LAS bf16x8*)(kb + 32 * 144 + ds * 32); }
;                     const LAS unsigned char* vb = lds + (t & 1) * AT_BUF + AT_KB + n32 * 144 + hi * 16;
;                     bf16x8 vf[2][4];
; #pragma unroll
;                     for (int i = 0; i < 4; ++i) vf[0][i] = *(const LAS bf16x8*)(vb + i * 32 * 144);
;                     __builtin_amdgcn_sched_barrier(0);
;                     #pragma unroll
;                     for (int ds = 0; ds < 4; ++ds) {
;                         p0 = __builtin_amdgcn_mfma_f32_32x32x16_bf16(kf0[ds], qf[ds], p0, 0, 0, 0);
;                         p1 = __builtin_amdgcn_mfma_f32_32x32x16_bf16(kf1[ds], qf[ds], p1, 0, 0, 0);
;                     }
;                                         __builtin_amdgcn_sched_barrier(0);
;                     if (t == td) {
;                         asm volatile("" ::: "memory");
; #pragma unroll
;                         for (int r = 0; r < 16; ++r) { const int key = (r & 3) + 8 * (r >> 2) + 4 * hi; if (key > qloc) p0[r] = -INFINITY; if (key + 32 > qloc) p1[r] = -INFINITY; }
;                     }
.LBB0_127:
	v_add_u32_e32 v0, v161, v160
	ds_read_b128 v[80:83], v0 offset:27648
	ds_read_b128 v[198:201], v0 offset:27680
	ds_read_b128 v[84:87], v0 offset:32256
	ds_read_b128 v[202:205], v0 offset:32288
	ds_read_b128 v[206:209], v0 offset:27712
	ds_read_b128 v[210:213], v0 offset:27744
	ds_read_b128 v[218:221], v0 offset:32320
	ds_read_b128 v[222:225], v0 offset:32352
	ds_read_b128 v[152:155], v0 offset:36864
	ds_read_b128 v[10:13], v0 offset:41472
	ds_read_b128 v[6:9], v0 offset:46080
	ds_read_b128 v[2:5], v0 offset:50688
	s_waitcnt lgkmcnt(11)
	v_mfma_f32_32x32x16_bf16 v[96:111], v[80:83], v[112:115], v[226:241]
	s_waitcnt lgkmcnt(9)
	v_mfma_f32_32x32x16_bf16 v[80:95], v[84:87], v[112:115], v[226:241]
	v_mfma_f32_32x32x16_bf16 v[96:111], v[198:201], v[116:119], v[96:111]
	s_waitcnt lgkmcnt(8)
	v_mfma_f32_32x32x16_bf16 v[80:95], v[202:205], v[116:119], v[80:95]
	s_waitcnt lgkmcnt(7)
	v_mfma_f32_32x32x16_bf16 v[96:111], v[206:209], v[120:123], v[96:111]
	s_waitcnt lgkmcnt(5)
	v_mfma_f32_32x32x16_bf16 v[80:95], v[218:221], v[120:123], v[80:95]
	v_mfma_f32_32x32x16_bf16 v[96:111], v[210:213], v[124:127], v[96:111]
	s_waitcnt lgkmcnt(4)
	v_mfma_f32_32x32x16_bf16 v[80:95], v[222:225], v[124:127], v[80:95]
	ds_read_b128 v[198:201], v0 offset:36896
	ds_read_b128 v[202:205], v0 offset:41504
	ds_read_b128 v[206:209], v0 offset:46112
	ds_read_b128 v[210:213], v0 offset:50720
	s_nop 7
	s_cmp_lg_u32 s31, s2
	s_cbranch_scc1 .Lat_nodiag_b
	v_cndmask_b32_e64 v14, v96, v248, s[42:43]
	v_cndmask_b32_e64 v80, v80, v248, s[44:45]
	v_cndmask_b32_e64 v97, v248, v97, s[46:47]
	v_cndmask_b32_e64 v96, v14, v96, s[46:47]
	v_cndmask_b32_e64 v81, v81, v248, s[48:49]
	v_cndmask_b32_e64 v98, v98, v248, s[50:51]
	v_cndmask_b32_e64 v82, v82, v248, s[52:53]
	v_cndmask_b32_e64 v99, v99, v248, s[54:55]
	v_cndmask_b32_e64 v83, v83, v248, s[56:57]
	v_cndmask_b32_e64 v100, v100, v248, s[58:59]
	v_cndmask_b32_e64 v84, v84, v248, s[60:61]
	v_cndmask_b32_e64 v101, v101, v248, s[62:63]
	v_cndmask_b32_e64 v85, v85, v248, s[64:65]
	v_cndmask_b32_e64 v102, v102, v248, s[66:67]
	v_cndmask_b32_e64 v86, v86, v248, s[68:69]
	v_cndmask_b32_e64 v103, v103, v248, s[70:71]
	v_cndmask_b32_e64 v87, v87, v248, s[72:73]
	v_cndmask_b32_e64 v104, v104, v248, s[74:75]
	v_cndmask_b32_e64 v88, v88, v248, s[76:77]
	v_cndmask_b32_e64 v105, v105, v248, s[78:79]
	v_cndmask_b32_e64 v89, v89, v248, s[80:81]
	v_cndmask_b32_e64 v106, v106, v248, s[82:83]
	v_cndmask_b32_e64 v90, v90, v248, s[84:85]
	v_cndmask_b32_e64 v107, v107, v248, s[86:87]
	v_cndmask_b32_e64 v91, v91, v248, s[88:89]
	v_cndmask_b32_e64 v108, v108, v248, s[90:91]
	v_cndmask_b32_e64 v92, v92, v248, s[92:93]
	v_cndmask_b32_e64 v109, v109, v248, s[94:95]
	v_cndmask_b32_e64 v93, v93, v248, s[96:97]
	v_cndmask_b32_e64 v110, v110, v248, s[6:7]
	v_cndmask_b32_e64 v94, v94, v248, s[8:9]
	v_cndmask_b32_e64 v111, v111, v248, s[10:11]
	v_cndmask_b32_e64 v95, v95, v248, s[12:13]

; #define LAS __attribute__((address_space(3)))
; __device__ __forceinline__ void attn_phase(const Args& a, LAS unsigned char* lds, const bf16* Qn, const bf16* Kn, const bf16* Vt, bf16* O, float* stash, int tid, int lane, int wave) {
;     ...
;                         const f32x2 mm2 = {mrun, mrun};
; #pragma unroll
;                         for (int r = 0; r < 16; r += 2) { const f32x2 a2 = (f32x2){p0[r], p0[r + 1]} - mm2, b2 = (f32x2){p1[r], p1[r + 1]} - mm2; p0[r] = a2.x; p0[r + 1] = a2.y; p1[r] = b2.x; p1[r + 1] = b2.y; }
;                     }
; #pragma unroll
;                     for (int r = 0; r < 16; ++r) { p0[r] = __builtin_amdgcn_exp2f(p0[r]); p1[r] = __builtin_amdgcn_exp2f(p1[r]); }
;                     {
;                         const f32x16 ps = p0 + p1;
;                         f32x2 s2 = (f32x2){ps[0], ps[1]} + (f32x2){ps[2], ps[3]};
; #pragma unroll
;                         for (int r = 4; r < 16; r += 2) s2 += (f32x2){ps[r], ps[r + 1]};
;                         lsum += s2.x + s2.y;
;                     }
;                     bf16x8 pf[4];
; #pragma unroll
;                     for (int s4 = 0; s4 < 4; ++s4) {
;                         u32x4 w;
;                         if (s4 < 2) { w.x = pk2(p0[8 * s4 + 0], p0[8 * s4 + 1]); w.y = pk2(p0[8 * s4 + 2], p0[8 * s4 + 3]); w.z = pk2(p0[8 * s4 + 4], p0[8 * s4 + 5]); w.w = pk2(p0[8 * s4 + 6], p0[8 * s4 + 7]); }
;                         else { const int q = s4 - 2; w.x = pk2(p1[8 * q + 0], p1[8 * q + 1]); w.y = pk2(p1[8 * q + 2], p1[8 * q + 3]); w.z = pk2(p1[8 * q + 4], p1[8 * q + 5]); w.w = pk2(p1[8 * q + 6], p1[8 * q + 7]); }
;                         pf[s4] = __builtin_bit_cast(bf16x8, w);
;                     }
; #pragma unroll
;                     for (int s4 = 0; s4 < 4; ++s4) {
;                         if (s4 + 1 < 4) {
; #pragma unroll
;                             for (int i = 0; i < 4; ++i) vf[(s4 + 1) & 1][i] = *(const LAS bf16x8*)(vb + i * 32 * 144 + (s4 + 1) * 32);
;                         }
;                         __builtin_amdgcn_sched_barrier(0);
;                         #pragma unroll
;                         for (int i = 0; i < 4; ++i) o[i] = __builtin_amdgcn_mfma_f32_32x32x16_bf16(vf[s4 & 1][i], pf[s4], o[i], 0, 0, 0);
;                                                 __builtin_amdgcn_sched_barrier(0);
;                     }
;                 }
.Lat_noresc_b:
	v_exp_f32_e32 v96, v96
	v_exp_f32_e32 v97, v97
	v_exp_f32_e32 v98, v98
	v_exp_f32_e32 v99, v99
	v_exp_f32_e32 v100, v100
	v_exp_f32_e32 v101, v101
	v_exp_f32_e32 v102, v102
	v_exp_f32_e32 v103, v103
	v_add_f32_e32 v214, v96, v97
	v_add_f32_e32 v215, v98, v99
	v_add_f32_e32 v214, v214, v100
	v_add_f32_e32 v215, v215, v101
	v_add_f32_e32 v214, v214, v102
	v_add_f32_e32 v215, v215, v103
	v_cvt_pk_bf16_f32 v218, v96, v97
	v_cvt_pk_bf16_f32 v219, v98, v99
	v_cvt_pk_bf16_f32 v220, v100, v101
	v_cvt_pk_bf16_f32 v221, v102, v103
	v_add_f32_e32 v197, v197, v214
	v_add_f32_e32 v197, v197, v215
	s_waitcnt lgkmcnt(7)
	v_mfma_f32_32x32x16_bf16 v[64:79], v[152:155], v[218:221], v[64:79]
	v_exp_f32_e32 v104, v104
	v_exp_f32_e32 v105, v105
	v_exp_f32_e32 v106, v106
	v_exp_f32_e32 v107, v107
	v_exp_f32_e32 v108, v108
	s_waitcnt lgkmcnt(6)
	v_mfma_f32_32x32x16_bf16 v[48:63], v[10:13], v[218:221], v[48:63]
	v_exp_f32_e32 v109, v109
	v_exp_f32_e32 v110, v110
	v_exp_f32_e32 v111, v111
	v_add_f32_e32 v214, v104, v105
	v_add_f32_e32 v215, v106, v107
	s_waitcnt lgkmcnt(5)
	v_mfma_f32_32x32x16_bf16 v[32:47], v[6:9], v[218:221], v[32:47]
	v_add_f32_e32 v214, v214, v108
	v_add_f32_e32 v215, v215, v109
	v_add_f32_e32 v214, v214, v110
	v_add_f32_e32 v215, v215, v111
	v_cvt_pk_bf16_f32 v222, v104, v105
	s_waitcnt lgkmcnt(4)
	v_mfma_f32_32x32x16_bf16 v[16:31], v[2:5], v[218:221], v[16:31]
	v_cvt_pk_bf16_f32 v223, v106, v107
	v_cvt_pk_bf16_f32 v224, v108, v109
	v_cvt_pk_bf16_f32 v225, v110, v111
	v_add_f32_e32 v197, v197, v214
	v_add_f32_e32 v197, v197, v215
	ds_read_b128 v[152:155], v0 offset:36928
	ds_read_b128 v[10:13], v0 offset:41536
	ds_read_b128 v[6:9], v0 offset:46144
	ds_read_b128 v[2:5], v0 offset:50752
	s_waitcnt lgkmcnt(7)
	v_mfma_f32_32x32x16_bf16 v[64:79], v[198:201], v[222:225], v[64:79]
	v_exp_f32_e32 v80, v80
	v_exp_f32_e32 v81, v81
	v_exp_f32_e32 v82, v82
	v_exp_f32_e32 v83, v83
	v_exp_f32_e32 v84, v84
	s_waitcnt lgkmcnt(6)
	v_mfma_f32_32x32x16_bf16 v[48:63], v[202:205], v[222:225], v[48:63]
	v_exp_f32_e32 v85, v85
	v_exp_f32_e32 v86, v86
	v_exp_f32_e32 v87, v87
	v_add_f32_e32 v214, v80, v81
	v_add_f32_e32 v215, v82, v83
	s_waitcnt lgkmcnt(5)
	v_mfma_f32_32x32x16_bf16 v[32:47], v[206:209], v[222:225], v[32:47]
	v_add_f32_e32 v214, v214, v84
	v_add_f32_e32 v215, v215, v85
	v_add_f32_e32 v214, v214, v86
	v_add_f32_e32 v215, v215, v87
	v_cvt_pk_bf16_f32 v218, v80, v81
	s_waitcnt lgkmcnt(4)
	v_mfma_f32_32x32x16_bf16 v[16:31], v[210:213], v[222:225], v[16:31]
	v_cvt_pk_bf16_f32 v219, v82, v83
	v_cvt_pk_bf16_f32 v220, v84, v85
	v_cvt_pk_bf16_f32 v221, v86, v87
	v_add_f32_e32 v197, v197, v214
	v_add_f32_e32 v197, v197, v215
	ds_read_b128 v[198:201], v0 offset:36960
	ds_read_b128 v[202:205], v0 offset:41568
	ds_read_b128 v[206:209], v0 offset:46176
	ds_read_b128 v[210:213], v0 offset:50784
	s_waitcnt lgkmcnt(7)
	v_mfma_f32_32x32x16_bf16 v[64:79], v[152:155], v[218:221], v[64:79]
	v_exp_f32_e32 v88, v88
	v_exp_f32_e32 v89, v89
	v_exp_f32_e32 v90, v90
	v_exp_f32_e32 v91, v91
	v_exp_f32_e32 v92, v92
	s_waitcnt lgkmcnt(6)
	v_mfma_f32_32x32x16_bf16 v[48:63], v[10:13], v[218:221], v[48:63]
	v_exp_f32_e32 v93, v93
	v_exp_f32_e32 v94, v94
	v_exp_f32_e32 v95, v95
	v_add_f32_e32 v214, v88, v89
	v_add_f32_e32 v215, v90, v91
	s_waitcnt lgkmcnt(5)
	v_mfma_f32_32x32x16_bf16 v[32:47], v[6:9], v[218:221], v[32:47]
	v_add_f32_e32 v214, v214, v92
	v_add_f32_e32 v215, v215, v93
	v_add_f32_e32 v214, v214, v94
	v_add_f32_e32 v215, v215, v95
	v_cvt_pk_bf16_f32 v222, v88, v89
	s_waitcnt lgkmcnt(4)
	v_mfma_f32_32x32x16_bf16 v[16:31], v[2:5], v[218:221], v[16:31]
	v_cvt_pk_bf16_f32 v223, v90, v91
	v_cvt_pk_bf16_f32 v224, v92, v93
	v_cvt_pk_bf16_f32 v225, v94, v95
	v_add_f32_e32 v197, v197, v214
	v_add_f32_e32 v197, v197, v215
	s_waitcnt lgkmcnt(3)
	v_mfma_f32_32x32x16_bf16 v[64:79], v[198:201], v[222:225], v[64:79]
	s_waitcnt lgkmcnt(2)
	v_mfma_f32_32x32x16_bf16 v[48:63], v[202:205], v[222:225], v[48:63]
	s_waitcnt lgkmcnt(1)
	v_mfma_f32_32x32x16_bf16 v[32:47], v[206:209], v[222:225], v[32:47]
	s_waitcnt lgkmcnt(0)
	v_mfma_f32_32x32x16_bf16 v[16:31], v[210:213], v[222:225], v[16:31]
	s_cmp_gt_u32 s2, s39
	s_cbranch_scc0 .LBB0_123
	s_branch .LBB0_124

; __device__ __forceinline__ void attn_phase(const Args& a, LAS unsigned char* lds, const bf16* Qn, const bf16* Kn, const bf16* Vt, bf16* O, float* stash, int tid, int lane, int wave) {
;     ...
;     __builtin_amdgcn_s_setprio(0);
.LBB0_137:
	v_mov_b32_e32 v240, 1
	v_mov_b32_e32 v241, 0x1600
	s_setprio 0
	s_mov_b64 s[6:7], 0
